# strategy 'one static priority raise for the younger half': s_setprio 1 for waves 4-7 across the prompt-attention key-block loop, reset at loop exit
# baseline (speedup 1.0000x reference)
; #define LAS __attribute__((address_space(3)))
; #define LDS_WAIT() asm volatile("s_waitcnt lgkmcnt(0)" ::: "memory")
; __device__ __forceinline__ void attn_unit(Frame& F, int b, int h, int qt, int kb_lo, int nkb, const bf16* QB, const bf16* KB, const bf16* VT, bf16* OUT, float bias2, f32x4* part, float* tpart) {
;     LAS bf16* Ks = (LAS bf16*)F.lds;
;     LAS bf16* Vs = (LAS bf16*)(F.lds + 34816);
;     const int w = F.wave, lane = F.lane, li = lane & 15, g = lane >> 4, tid = F.tid;
;     const int q0 = qt * 128 + w * 16, qpos = q0 + li;
;     bf16x8 qf[4];
;     { const bf16* qp = QB + (size_t)(b * SEQ + qpos) * BW + h * 128 + 8 * g;
; #pragma unroll
;       for (int ks = 0; ks < 4; ++ks) qf[ks] = *(const bf16x8*)(qp + 32 * ks); }
;     f32x4 oacc[8];
; #pragma unroll
;     for (int dt = 0; dt < 8; ++dt) oacc[dt] = (f32x4){0.f, 0.f, 0.f, 0.f};
;     float carry = 1.f;
;     const int kr0 = tid >> 4, kc0 = (tid & 15) * 8;
;     const int vr0 = tid >> 3, vc0 = (tid & 7) * 8;
;     const bf16* kg = KB + (size_t)(b * SEQ) * BW + h * 128 + kc0;
;     const bf16* vg = VT + (size_t)((b * 4 + h) * 128) * SEQ + vc0;
;     u32x4 lk[2], lv[2];
;     { const int kb = kb_lo + nkb - 1;
;       lk[0] = *(const u32x4*)(kg + (size_t)(kb * 64 + kr0) * BW); lk[1] = *(const u32x4*)(kg + (size_t)(kb * 64 + kr0 + 32) * BW);
;       lv[0] = *(const u32x4*)(vg + (size_t)vr0 * SEQ + kb * 64); lv[1] = *(const u32x4*)(vg + (size_t)(vr0 + 64) * SEQ + kb * 64);
;       *(LAS u32x4*)(Ks + kr0 * 136 + kc0) = lk[0]; *(LAS u32x4*)(Ks + (kr0 + 32) * 136 + kc0) = lk[1];
;       *(LAS u32x4*)(Vs + vr0 * 72 + vc0) = lv[0]; *(LAS u32x4*)(Vs + (vr0 + 64) * 72 + vc0) = lv[1]; }
;     LDS_WAIT(); __syncthreads();
.LBB0_1057:
	v_readlane_b32 s0, v252, 42
	s_lshl_b32 s20, s0, 1
	v_readlane_b32 s0, v252, 48
	v_lshlrev_b32_e64 v4, 4, s18
	v_readlane_b32 s1, v252, 49
	s_add_u32 s0, s10, s0
	v_lshl_add_u32 v118, s5, 7, v4
	v_lshlrev_b32_e32 v4, 3, v1
	s_addc_u32 s1, s11, s1
	v_and_b32_e32 v5, 0x78, v4
	s_add_u32 s0, s0, s20
	s_addc_u32 s1, s1, 0
	v_lshlrev_b32_e32 v34, 1, v5
	v_ashrrev_i32_e32 v119, 4, v1
	v_ashrrev_i32_e32 v20, 3, v1
	v_and_b32_e32 v1, 56, v4
	v_lshl_add_u64 v[4:5], s[0:1], 0, v[34:35]
	s_mov_b64 s[0:1], 0x33600000
	v_lshl_add_u64 v[78:79], v[4:5], 0, s[0:1]
	v_readlane_b32 s0, v252, 43
	v_readlane_b32 s1, v252, 44
	s_add_u32 s0, s10, s0
	s_addc_u32 s1, s11, s1
	s_add_i32 s19, s2, s4
	s_lshl_b32 s2, s19, 6
	v_add_u32_e32 v4, s2, v119
	v_ashrrev_i32_e32 v5, 31, v4
	v_lshlrev_b32_e32 v80, 1, v1
	v_mov_b32_e32 v81, v35
	v_lshlrev_b64 v[4:5], 10, v[4:5]
	v_ashrrev_i32_e32 v21, 31, v20
	v_lshl_add_u64 v[12:13], s[0:1], 0, v[80:81]
	v_lshl_add_u64 v[4:5], v[78:79], 0, v[4:5]
	s_mov_b32 s0, 0x8000
	v_lshlrev_b64 v[14:15], 13, v[20:21]
	v_add_co_u32_e32 v8, vcc, s0, v4
	v_lshl_add_u64 v[12:13], v[12:13], 0, v[14:15]
	s_mov_b64 s[0:1], 0x33e00000
	s_mov_b32 s3, s21
	s_mov_b64 s[6:7], 0x33e80000
	v_and_b32_e32 v3, 15, v122
	v_lshl_add_u64 v[82:83], v[12:13], 0, s[0:1]
	s_lshl_b64 s[0:1], s[2:3], 1
	v_lshl_add_u64 v[84:85], v[12:13], 0, s[6:7]
	v_lshl_add_u64 v[14:15], v[82:83], 0, s[0:1]
	v_lshl_add_u64 v[16:17], v[84:85], 0, s[0:1]
	v_or_b32_e32 v76, v118, v3
	v_readlane_b32 s0, v252, 46
	v_ashrrev_i32_e32 v30, 4, v122
	v_lshlrev_b32_e32 v26, 3, v30
	v_add_u32_e32 v22, s0, v76
	v_ashrrev_i32_e32 v23, 31, v22
	v_lshlrev_b64 v[24:25], 10, v[22:23]
	v_lshl_add_u64 v[24:25], s[10:11], 0, v[24:25]
	v_readlane_b32 s1, v252, 47
	v_lshl_add_u64 v[24:25], v[24:25], 0, s[20:21]
	v_ashrrev_i32_e32 v27, 31, v26
	v_addc_co_u32_e32 v9, vcc, 0, v5, vcc
	v_lshl_add_u64 v[24:25], v[26:27], 1, v[24:25]
	s_mov_b64 s[0:1], 0x32e00000
	global_load_dwordx4 v[4:7], v[4:5], off
	s_nop 0
	global_load_dwordx4 v[8:11], v[8:9], off
	s_nop 0
	global_load_dwordx4 v[12:15], v[14:15], off
	s_nop 0
	global_load_dwordx4 v[16:19], v[16:17], off
	v_lshl_add_u64 v[28:29], v[24:25], 0, s[0:1]
	s_mov_b32 s0, 0x32e00000
	v_add_co_u32_e32 v24, vcc, s0, v24
	s_movk_i32 s3, 0x88
	s_nop 0
	v_addc_co_u32_e32 v25, vcc, 0, v25, vcc
	global_load_dwordx4 v[44:47], v[28:29], off offset:64
	global_load_dwordx4 v[40:43], v[28:29], off offset:128
	global_load_dwordx4 v[48:51], v[24:25], off
	global_load_dwordx4 v[36:39], v[28:29], off offset:192
	s_waitcnt vmcnt(8)
	v_mul_f32_e32 v52, 0x3fb8aa3b, v2
	v_mul_lo_u32 v2, v119, s3
	s_movk_i32 s3, 0x48
	v_mul_lo_u32 v20, v20, s3
	v_lshlrev_b32_e32 v125, 1, v2
	v_lshlrev_b32_e32 v126, 1, v20
	v_add3_u32 v2, 0, v125, v34
	v_and_b32_e32 v1, -16, v122
	v_mul_u32_u24_e32 v121, 0x110, v3
	v_mul_u32_u24_e32 v73, 0x90, v3
	v_add3_u32 v3, 0, v126, v80
	v_add_u32_e32 v120, 0, v1
	v_lshlrev_b32_e32 v72, 2, v30
	v_cmp_ne_u32_e64 s[38:39], 1, v30
	v_cmp_eq_u32_e32 vcc, 2, v30
	v_sub_u32_e32 v77, v120, v26
	v_lshlrev_b64 v[74:75], 9, v[22:23]
	s_mov_b32 s24, 0
	v_cmp_lt_u32_e64 s[0:1], 15, v122
	v_mov_b32_e32 v53, v52
	v_mov_b32_e32 v54, v52
	v_mov_b32_e32 v55, v52
	v_or_b32_e32 v124, 15, v118
	v_mov_b32_e32 v1, v76
	s_add_i32 s25, s4, -1
	s_or_b32 s26, s2, 63
	s_waitcnt vmcnt(7)
	ds_write_b128 v2, v[4:7]
	s_waitcnt vmcnt(6)
	ds_write_b128 v2, v[8:11] offset:8704
	s_waitcnt vmcnt(5)
	ds_write_b128 v3, v[12:15] offset:34816
	s_waitcnt vmcnt(4)
	ds_write_b128 v3, v[16:19] offset:44032
	s_waitcnt lgkmcnt(0)
	v_mov_b32_e32 v4, v35
	v_mov_b32_e32 v5, v35
	v_mov_b32_e32 v2, v35
	v_mov_b32_e32 v3, v35
	v_mov_b64_e32 v[8:9], v[4:5]
	v_mov_b64_e32 v[12:13], v[4:5]
	v_mov_b64_e32 v[16:17], v[4:5]
	v_mov_b64_e32 v[20:21], v[4:5]
	v_mov_b64_e32 v[24:25], v[4:5]
	v_mov_b64_e32 v[28:29], v[4:5]
	v_mov_b64_e32 v[32:33], v[4:5]
	v_mov_b32_e32 v81, 1.0
	v_mov_b64_e32 v[6:7], v[2:3]
	v_mov_b64_e32 v[10:11], v[2:3]
	v_mov_b64_e32 v[14:15], v[2:3]
	v_mov_b64_e32 v[18:19], v[2:3]
	v_mov_b64_e32 v[22:23], v[2:3]
	v_mov_b64_e32 v[26:27], v[2:3]
	v_mov_b64_e32 v[30:31], v[2:3]
	s_cmp_lt_u32 s18, 4
	s_cbranch_scc1 .Lattn_prio_done
	s_setprio 1
.Lattn_prio_done:
	s_waitcnt lgkmcnt(0)
	s_barrier
	s_branch .LBB0_1060

; #define LAS __attribute__((address_space(3)))
; __device__ __forceinline__ float ex2(float x) { return __builtin_amdgcn_exp2f(x); }
; __device__ __forceinline__ float rcpf_(float x) { return __builtin_amdgcn_rcpf(x); }
; __device__ __forceinline__ void attn_unit(Frame& F, int b, int h, int qt, int kb_lo, int nkb, const bf16* QB, const bf16* KB, const bf16* VT, bf16* OUT, float bias2, f32x4* part, float* tpart) {
;     ...
;         if (kb * 64 < q0 + 15) {
;             const LAS bf16* Kb = Ks + buf * (64 * 136); const LAS bf16* Vb = Vs + buf * (128 * 72);
;             f32x4 s[4];
; #pragma unroll
;             for (int st = 0; st < 4; ++st) { s[st] = (f32x4){bias2, bias2, bias2, bias2};
; #pragma unroll
;                 for (int ks = 0; ks < 4; ++ks) { const bf16x8 af = *(const LAS bf16x8*)(Kb + (16 * st + li) * 136 + 32 * ks + 8 * g); s[st] = __builtin_amdgcn_mfma_f32_16x16x32_bf16(af, qf[ks], s[st], 0, 0, 0); } }
;             float om[4][4], bt[4][4], lt[4], X[4], GT[4];
;             if (kb * 64 + 63 >= q0) {
;                 const int kbase = kb * 64 + 4 * g;
; #pragma unroll
;                 for (int st = 0; st < 4; ++st)
; #pragma unroll
;                     for (int r = 0; r < 4; ++r) { const float e = ex2(s[st][r]); float o = rcpf_(1.0f + e), bb = e * o;
;                         if (kbase + 16 * st + r >= qpos) { o = 1.f; bb = 0.f; }
;                         om[st][r] = o; bt[st][r] = bb; }
.LBB0_1102:
	s_setprio 0
	s_sub_i32 s2, s19, s25
	s_lshl_b32 s6, s2, 6
	v_cmp_lt_i32_e64 s[4:5], s6, v124
	s_and_saveexec_b64 s[2:3], s[4:5]
	s_cbranch_execz .LBB0_1140
	s_and_b32 s19, s25, 1
	s_mul_i32 s4, s19, 0x4400
	v_add3_u32 v34, v120, s4, v121
	ds_read_b128 v[56:59], v34
	ds_read_b128 v[60:63], v34 offset:64
	s_or_b32 s4, s6, 63
	v_cmp_ge_i32_e64 s[4:5], s4, v118
	s_waitcnt lgkmcnt(1)
	v_mfma_f32_16x16x32_bf16 v[56:59], v[56:59], v[48:51], v[52:55]
	ds_read_b128 v[64:67], v34 offset:4416
	ds_read_b128 v[68:71], v34 offset:8768
	s_waitcnt lgkmcnt(2)
	v_mfma_f32_16x16x32_bf16 v[56:59], v[60:63], v[44:47], v[56:59]
	ds_read_b128 v[60:63], v34 offset:128
	s_waitcnt lgkmcnt(0)
	v_mfma_f32_16x16x32_bf16 v[56:59], v[60:63], v[40:43], v[56:59]
	ds_read_b128 v[60:63], v34 offset:192
	s_waitcnt lgkmcnt(0)
	v_mfma_f32_16x16x32_bf16 v[56:59], v[60:63], v[36:39], v[56:59]
	ds_read_b128 v[60:63], v34 offset:4352
	s_nop 6
	v_exp_f32_e32 v97, v58
	v_exp_f32_e32 v96, v59
	s_waitcnt lgkmcnt(0)
	v_mfma_f32_16x16x32_bf16 v[60:63], v[60:63], v[48:51], v[52:55]
	v_add_f32_e32 v103, 1.0, v97
	v_add_f32_e32 v102, 1.0, v96
	v_mfma_f32_16x16x32_bf16 v[60:63], v[64:67], v[44:47], v[60:63]
	ds_read_b128 v[64:67], v34 offset:4480
	s_waitcnt lgkmcnt(0)
	v_mfma_f32_16x16x32_bf16 v[60:63], v[64:67], v[40:43], v[60:63]
	ds_read_b128 v[64:67], v34 offset:4544
	s_waitcnt lgkmcnt(0)
	v_mfma_f32_16x16x32_bf16 v[60:63], v[64:67], v[36:39], v[60:63]
	ds_read_b128 v[64:67], v34 offset:8704
	s_nop 6
	v_exp_f32_e32 v91, v62
	s_waitcnt lgkmcnt(0)
	v_mfma_f32_16x16x32_bf16 v[64:67], v[64:67], v[48:51], v[52:55]
	v_exp_f32_e32 v88, v63
	v_add_f32_e32 v99, 1.0, v91
	v_add_f32_e32 v98, 1.0, v88
	v_mfma_f32_16x16x32_bf16 v[64:67], v[68:71], v[44:47], v[64:67]
	ds_read_b128 v[68:71], v34 offset:8832
	s_waitcnt lgkmcnt(0)
	v_mfma_f32_16x16x32_bf16 v[64:67], v[68:71], v[40:43], v[64:67]
	ds_read_b128 v[68:71], v34 offset:8896
	s_waitcnt lgkmcnt(0)
	v_mfma_f32_16x16x32_bf16 v[68:71], v[68:71], v[36:39], v[64:67]
	s_nop 4
	ds_read_b128 v[64:67], v34 offset:13056
	s_nop 1
	v_exp_f32_e32 v62, v68
	s_waitcnt lgkmcnt(0)
	v_mfma_f32_16x16x32_bf16 v[48:51], v[64:67], v[48:51], v[52:55]
	s_nop 2
	ds_read_b128 v[52:55], v34 offset:13120
	v_exp_f32_e32 v66, v56
	v_exp_f32_e32 v67, v57
	s_waitcnt lgkmcnt(0)
	v_mfma_f32_16x16x32_bf16 v[44:47], v[52:55], v[44:47], v[48:51]
	s_nop 2
	ds_read_b128 v[48:51], v34 offset:13184
	v_exp_f32_e32 v64, v60
	v_exp_f32_e32 v65, v61
	s_waitcnt lgkmcnt(0)
	v_mfma_f32_16x16x32_bf16 v[40:43], v[48:51], v[40:43], v[44:47]
	s_nop 2
	ds_read_b128 v[44:47], v34 offset:13248
	v_exp_f32_e32 v63, v69
	v_exp_f32_e32 v87, v70
	s_waitcnt lgkmcnt(0)
	v_mfma_f32_16x16x32_bf16 v[36:39], v[44:47], v[36:39], v[40:43]
	v_exp_f32_e32 v84, v71
	v_add_f32_e32 v104, 1.0, v66
	v_add_f32_e32 v105, 1.0, v67
	s_nop 4
	v_exp_f32_e32 v60, v36
	v_exp_f32_e32 v61, v37
	v_exp_f32_e32 v83, v38
	v_exp_f32_e32 v82, v39
	v_add_f32_e32 v100, 1.0, v64
	v_add_f32_e32 v101, 1.0, v65
	v_add_f32_e32 v94, 1.0, v62
	v_add_f32_e32 v95, 1.0, v63
	v_add_f32_e32 v93, 1.0, v87
	v_add_f32_e32 v92, 1.0, v84
	v_add_f32_e32 v89, 1.0, v60
	v_add_f32_e32 v90, 1.0, v61
	v_add_f32_e32 v86, 1.0, v83
	v_add_f32_e32 v85, 1.0, v82
	s_and_saveexec_b64 s[16:17], s[4:5]
	s_xor_b64 s[16:17], exec, s[16:17]
	s_cbranch_execz .LBB0_1105
	v_rcp_f32_e32 v38, v104
	v_rcp_f32_e32 v39, v105
	v_add_u32_e32 v70, s6, v72
	v_rcp_f32_e32 v40, v103
	v_or_b32_e32 v34, 1, v70
	v_cmp_lt_i32_e64 s[6:7], v70, v76
	v_rcp_f32_e32 v42, v102
	v_pk_mul_f32 v[36:37], v[66:67], v[38:39]
	v_cmp_lt_i32_e64 s[4:5], v34, v1
	v_cndmask_b32_e64 v58, 1.0, v38, s[6:7]
	v_or_b32_e32 v38, 2, v70
	v_cndmask_b32_e64 v37, 0, v37, s[4:5]
	v_cndmask_b32_e64 v59, 1.0, v39, s[4:5]
	v_cmp_lt_i32_e64 s[4:5], v38, v76
	v_mul_f32_e32 v34, v97, v40
	v_or_b32_e32 v39, 3, v70
	v_cndmask_b32_e64 v80, 1.0, v40, s[4:5]
	v_rcp_f32_e32 v40, v100
	v_rcp_f32_e32 v41, v101
	v_cndmask_b32_e64 v34, 0, v34, s[4:5]
	v_mul_f32_e32 v38, v96, v42
	v_cmp_lt_i32_e64 s[4:5], v39, v76
	v_add_u32_e32 v44, 17, v70
	v_rcp_f32_e32 v46, v98
	v_cndmask_b32_e64 v39, 0, v38, s[4:5]
	v_cndmask_b32_e64 v38, 1.0, v42, s[4:5]
	v_cmp_lt_i32_e64 s[4:5], v44, v1
	v_rcp_f32_e32 v44, v99
	v_pk_mul_f32 v[42:43], v[64:65], v[40:41]
	v_add_u32_e32 v45, 16, v70
	v_cndmask_b32_e64 v57, 1.0, v41, s[4:5]
	v_add_u32_e32 v41, 18, v70
	v_cndmask_b32_e64 v36, 0, v36, s[6:7]
	v_cndmask_b32_e64 v43, 0, v43, s[4:5]
	v_cmp_lt_i32_e64 s[6:7], v45, v76
	v_cmp_lt_i32_e64 s[4:5], v41, v76
	v_add_u32_e32 v47, 19, v70
	v_cndmask_b32_e64 v56, 1.0, v40, s[6:7]
	v_mul_f32_e32 v40, v91, v44
	v_cndmask_b32_e64 v79, 1.0, v44, s[4:5]
	v_rcp_f32_e32 v44, v94
	v_rcp_f32_e32 v45, v95
	v_cndmask_b32_e64 v40, 0, v40, s[4:5]
	v_mul_f32_e32 v41, v88, v46
	v_cmp_lt_i32_e64 s[4:5], v47, v76
	v_add_u32_e32 v48, 33, v70
	v_add_u32_e32 v49, 32, v70
	v_cndmask_b32_e64 v41, 0, v41, s[4:5]
	v_cndmask_b32_e64 v68, 1.0, v46, s[4:5]
	v_cmp_lt_i32_e64 s[4:5], v48, v1
	v_rcp_f32_e32 v48, v93
	v_pk_mul_f32 v[46:47], v[62:63], v[44:45]
	v_cndmask_b32_e64 v55, 1.0, v45, s[4:5]
	v_add_u32_e32 v45, 34, v70
	v_rcp_f32_e32 v50, v92
	v_cndmask_b32_e64 v42, 0, v42, s[6:7]
	v_cndmask_b32_e64 v47, 0, v47, s[4:5]
	v_cmp_lt_i32_e64 s[6:7], v49, v76
	v_cmp_lt_i32_e64 s[4:5], v45, v76
	v_rcp_f32_e32 v49, v90
	v_cndmask_b32_e64 v54, 1.0, v44, s[6:7]
	v_mul_f32_e32 v44, v87, v48
	v_cndmask_b32_e64 v78, 1.0, v48, s[4:5]
	v_rcp_f32_e32 v48, v89
	v_add_u32_e32 v51, 35, v70
	v_cndmask_b32_e64 v44, 0, v44, s[4:5]
	v_mul_f32_e32 v45, v84, v50
	v_cmp_lt_i32_e64 s[4:5], v51, v76
	v_add_u32_e32 v52, 49, v70
	v_add_u32_e32 v53, 48, v70
	v_cndmask_b32_e64 v45, 0, v45, s[4:5]
	v_cndmask_b32_e64 v69, 1.0, v50, s[4:5]
	v_cmp_lt_i32_e64 s[4:5], v52, v1
	v_rcp_f32_e32 v1, v86
	v_pk_mul_f32 v[50:51], v[60:61], v[48:49]
	v_rcp_f32_e32 v60, v85
	v_cndmask_b32_e64 v46, 0, v46, s[6:7]
	v_cmp_lt_i32_e64 s[6:7], v53, v76
	v_cndmask_b32_e64 v53, 1.0, v49, s[4:5]
	v_add_u32_e32 v49, 50, v70
	v_cndmask_b32_e64 v51, 0, v51, s[4:5]
	v_cndmask_b32_e64 v52, 1.0, v48, s[6:7]
	v_mul_f32_e32 v48, v83, v1
	v_cmp_lt_i32_e64 s[4:5], v49, v76
	v_add_u32_e32 v49, 51, v70
	v_cndmask_b32_e64 v50, 0, v50, s[6:7]
	v_cndmask_b32_e64 v48, 0, v48, s[4:5]
	v_cndmask_b32_e64 v71, 1.0, v1, s[4:5]
	v_mul_f32_e32 v1, v82, v60
	v_cmp_lt_i32_e64 s[4:5], v49, v76
	s_nop 1
	v_cndmask_b32_e64 v49, 0, v1, s[4:5]
	v_cndmask_b32_e64 v70, 1.0, v60, s[4:5]
